# MLA smax loop: waves 4-7 run a copy with the LDS refill and barrier between QK and softmax (half-step stagger against waves 0-3)
# baseline (speedup 1.0000x reference)
; template <int DQK, bool NA, bool SMAX, int LDV> ...
;     ...
;   u32x4 rkA[NKC], rvA, rkB[NKC], rvB;
;   int kkey[NKC], kcc[NKC];
;   bool kval[NKC];
; #pragma unroll
;   for (int i = 0; i < NKC; ++i) { const int c = tid + i * 512; kval[i] = c < 64 * CPK; kkey[i] = kval[i] ? c / CPK : 0; kcc[i] = kval[i] ? c - kkey[i] * CPK : 0; }
;   const int vdv = tid >> 3, vcc = tid & 7;
;   {
; #pragma unroll
;     for (int i = 0; i < NKC; ++i) rkA[i] = *(const u32x4*)(Kp + (size_t)kkey[i] * ldk + kcc[i] * 8);
;     rvA = *(const u32x4*)(Vp + (size_t)vdv * LDV + vcc * 8);
;     if (nkt > 1) {
;       const int kb = 64;
; #pragma unroll
;       for (int i = 0; i < NKC; ++i) rkB[i] = *(const u32x4*)(Kp + (size_t)(kb + kkey[i]) * ldk + kcc[i] * 8);
;       rvB = *(const u32x4*)(Vp + (size_t)(kb + vdv) * LDV + vcc * 8);
;     }
; #pragma unroll
;     for (int i = 0; i < NKC; ++i) if (kval[i]) *(u32x4*)(smem + kkey[i] * KSTR + kcc[i] * 16) = rkA[i];
;     *(u32x4*)(smem + KBYTES + vdv * VSTR + vcc * 16) = rvA;
;   }
;   __syncthreads();
;   f32x4 o[4][2];
;   float mrun[2], lrun[2];
; #pragma unroll
;   for (int qt = 0; qt < 2; ++qt) {
;     mrun[qt] = -1e30f; lrun[qt] = 0.f;
; #pragma unroll
;     for (int d = 0; d < 4; ++d) o[d][qt] = (f32x4){0.f, 0.f, 0.f, 0.f};
;   }
.LBB0_1133:
	s_or_b64 exec, exec, s[4:5]
	s_movk_i32 s26, 0x600
	v_mad_i64_i32 v[64:65], s[4:5], v14, s26, 0
	v_mad_i64_i32 v[14:15], s[4:5], v15, s26, 0
	s_movk_i32 s4, 0xa0
	s_nop 0
	v_mul_lo_u32 v6, v6, s4
	v_add_u32_e32 v6, 0, v6
	v_add_u32_e32 v173, v6, v0
	v_lshlrev_b32_e32 v172, 2, v13
	v_lshrrev_b32_e32 v6, 2, v12
	s_add_u32 s4, s53, s52
	v_or_b32_e32 v6, v172, v6
	s_addc_u32 s5, 0, 0
	v_lshl_add_u32 v11, v13, 4, 0
	v_mul_u32_u24_e32 v13, 0xa0, v6
	v_add_u32_e32 v174, 0, v7
	v_lshl_add_u64 v[6:7], s[4:5], 0, v[8:9]
	s_add_u32 s4, s33, s19
	s_addc_u32 s5, 0, 0
	v_mul_u32_u24_e32 v66, 0xe0, v12
	v_lshlrev_b32_e32 v12, 3, v12
	v_lshl_add_u64 v[120:121], v[6:7], 0, v[0:1]
	v_lshl_add_u64 v[6:7], s[4:5], 0, v[14:15]
	v_and_b32_e32 v12, 24, v12
	v_lshl_add_u64 v[124:125], v[4:5], 1, v[6:7]
	v_lshl_add_u64 v[4:5], s[4:5], 0, v[64:65]
	v_add_u32_e32 v12, 0, v12
	v_lshl_add_u64 v[126:127], v[2:3], 1, v[4:5]
	v_mov_b32_e32 v4, 0
	v_ashrrev_i32_e32 v119, 31, v118
	v_ashrrev_i32_e32 v117, 31, v116
	v_add_u32_e32 v175, 0, v10
	s_mov_b32 s19, 0
	v_add_u32_e32 v0, v11, v66
	v_add_u32_e32 v176, v12, v13
	v_mov_b32_e32 v5, v4
	v_mov_b32_e32 v6, v4
	v_mov_b32_e32 v7, v4
	v_mov_b32_e32 v64, v4
	v_mov_b32_e32 v65, v4
	v_mov_b32_e32 v66, v4
	v_mov_b32_e32 v67, v4
	v_mov_b32_e32 v8, v4
	v_mov_b32_e32 v9, v4
	v_mov_b32_e32 v10, v4
	v_mov_b32_e32 v11, v4
	v_mov_b32_e32 v68, v4
	v_mov_b32_e32 v69, v4
	v_mov_b32_e32 v70, v4
	v_mov_b32_e32 v71, v4
	v_mov_b32_e32 v12, v4
	v_mov_b32_e32 v13, v4
	v_mov_b32_e32 v14, v4
	v_mov_b32_e32 v15, v4
	v_mov_b32_e32 v76, v4
	v_mov_b32_e32 v77, v4
	v_mov_b32_e32 v78, v4
	v_mov_b32_e32 v79, v4
	v_mov_b32_e32 v72, v4
	v_mov_b32_e32 v73, v4
	v_mov_b32_e32 v74, v4
	v_mov_b32_e32 v75, v4
	v_mov_b32_e32 v80, v4
	v_mov_b32_e32 v81, v4
	v_mov_b32_e32 v82, v4
	v_mov_b32_e32 v83, v4
	v_mov_b32_e32 v122, v4
	v_mov_b32_e32 v123, v4
	s_waitcnt vmcnt(3)
	ds_write_b128 v173, v[52:55] offset:14336
	s_waitcnt lgkmcnt(0)
	s_barrier
	v_sub_f32_e32 v244, 0, v188
	v_sub_f32_e32 v245, 0, v188
	v_sub_f32_e32 v246, 0, v188
	v_sub_f32_e32 v247, 0, v188
	v_readfirstlane_b32 s100, v149
	s_nop 3
	s_cmpk_ge_u32 s100, 0x100
	s_cbranch_scc1 .Lmla_y_1136
	s_branch .LBB0_1136

; template <int DQK, bool NA, bool SMAX, int LDV> ...
;     ...
;     f32x4 s[4][2];
; #pragma unroll
;     for (int kt = 0; kt < 4; ++kt) { s[kt][0] = (f32x4){0.f, 0.f, 0.f, 0.f}; s[kt][1] = (f32x4){0.f, 0.f, 0.f, 0.f}; }
; #pragma unroll
;     for (int ds = 0; ds < NDS; ++ds) {
;       bf16x8 kf[4];
; #pragma unroll
;       for (int kt = 0; kt < 4; ++kt) kf[kt] = *(const bf16x8*)(ks + (kt * 16 + fr) * KSTR + ds * 64 + fq * 16);
; #pragma unroll
;       for (int kt = 0; kt < 4; ++kt) {
;         s[kt][0] = __builtin_amdgcn_mfma_f32_16x16x32_bf16(kf[kt], qf[0][ds], s[kt][0], 0, 0, 0);
;         s[kt][1] = __builtin_amdgcn_mfma_f32_16x16x32_bf16(kf[kt], qf[1][ds], s[kt][1], 0, 0, 0);
;       }
;     }
;     bf16x8 vfr[2][4];
; #pragma unroll
;     for (int k2 = 0; k2 < 2; ++k2)
; #pragma unroll
;       for (int d = 0; d < 4; ++d) {
;         const char* vp = vs + (k2 * 32 + fq * 4 + (fr >> 2)) * VSTR + d * 32 + (fr & 3) * 8;
;         typedef short s16x4_t __attribute__((ext_vector_type(4)));
;         const s16x4_t lo = __builtin_amdgcn_ds_read_tr16_b64_v4i16((__attribute__((address_space(3))) s16x4_t*)(vp));
;         const s16x4_t hi = __builtin_amdgcn_ds_read_tr16_b64_v4i16((__attribute__((address_space(3))) s16x4_t*)(vp + 16 * VSTR));
;         vfr[k2][d] = __builtin_shufflevector(lo, hi, 0, 1, 2, 3, 4, 5, 6, 7);
;       }
;     ...
; #pragma unroll
;     for (int k2 = 0; k2 < 2; ++k2) {
;       bf16x8 pf[2];
; #pragma unroll
;       for (int qt = 0; qt < 2; ++qt) {
;         u32x4 u;
;         u[0] = cvt_pk_bf16(s[2 * k2][qt][0], s[2 * k2][qt][1]); u[1] = cvt_pk_bf16(s[2 * k2][qt][2], s[2 * k2][qt][3]);
;         u[2] = cvt_pk_bf16(s[2 * k2 + 1][qt][0], s[2 * k2 + 1][qt][1]); u[3] = cvt_pk_bf16(s[2 * k2 + 1][qt][2], s[2 * k2 + 1][qt][3]);
;         pf[qt] = __builtin_bit_cast(bf16x8, u);
;       }
; #pragma unroll
;       for (int d = 0; d < 4; ++d) {
;         o[d][0] = __builtin_amdgcn_mfma_f32_16x16x32_bf16(vfr[k2][d], pf[0], o[d][0], 0, 0, 0);
;         o[d][1] = __builtin_amdgcn_mfma_f32_16x16x32_bf16(vfr[k2][d], pf[1], o[d][1], 0, 0, 0);
;       }
;     }
;     if (more) {
;       char* nx = smem + (cur ^ 1) * STG;
; #pragma unroll
;       for (int i = 0; i < NKC; ++i) if (kval[i]) *(u32x4*)(nx + kkey[i] * KSTR + kcc[i] * 16) = rk_wr[i];
;       *(u32x4*)(nx + KBYTES + vdv * VSTR + vcc * 16) = rv_wr;
;     }
.LBB0_1144:
	ds_read_b128 v[84:87], v0 offset:24576
	ds_read_b128 v[88:91], v0 offset:28160
	ds_read_b128 v[92:95], v0 offset:31744
	ds_read_b128 v[96:99], v0 offset:35328
	ds_read_b128 v[154:157], v0 offset:24640
	ds_read_b128 v[158:161], v0 offset:28224
	ds_read_b128 v[162:165], v0 offset:31808
	ds_read_b128 v[166:169], v0 offset:35392
	s_waitcnt lgkmcnt(7)
	v_mfma_f32_16x16x32_bf16 v[100:103], v[84:87], v[16:19], v[244:247]
	v_mfma_f32_16x16x32_bf16 v[84:87], v[84:87], v[28:31], v[244:247]
	s_waitcnt lgkmcnt(6)
	v_mfma_f32_16x16x32_bf16 v[104:107], v[88:91], v[16:19], v[244:247]
	v_mfma_f32_16x16x32_bf16 v[88:91], v[88:91], v[28:31], v[244:247]
	s_waitcnt lgkmcnt(5)
	v_mfma_f32_16x16x32_bf16 v[108:111], v[92:95], v[16:19], v[244:247]
	v_mfma_f32_16x16x32_bf16 v[92:95], v[92:95], v[28:31], v[244:247]
	s_waitcnt lgkmcnt(4)
	v_mfma_f32_16x16x32_bf16 v[112:115], v[96:99], v[16:19], v[244:247]
	v_mfma_f32_16x16x32_bf16 v[96:99], v[96:99], v[28:31], v[244:247]
	s_waitcnt lgkmcnt(3)
	v_mfma_f32_16x16x32_bf16 v[100:103], v[154:157], v[20:23], v[100:103]
	v_mfma_f32_16x16x32_bf16 v[84:87], v[154:157], v[32:35], v[84:87]
	s_waitcnt lgkmcnt(2)
	v_mfma_f32_16x16x32_bf16 v[104:107], v[158:161], v[20:23], v[104:107]
	v_mfma_f32_16x16x32_bf16 v[88:91], v[158:161], v[32:35], v[88:91]
	s_waitcnt lgkmcnt(1)
	v_mfma_f32_16x16x32_bf16 v[108:111], v[162:165], v[20:23], v[108:111]
	v_mfma_f32_16x16x32_bf16 v[92:95], v[162:165], v[32:35], v[92:95]
	s_waitcnt lgkmcnt(0)
	v_mfma_f32_16x16x32_bf16 v[112:115], v[166:169], v[20:23], v[112:115]
	v_mfma_f32_16x16x32_bf16 v[96:99], v[166:169], v[32:35], v[96:99]
	ds_read_b128 v[154:157], v0 offset:24704
	ds_read_b128 v[158:161], v0 offset:28288
	ds_read_b128 v[162:165], v0 offset:31872
	ds_read_b128 v[166:169], v0 offset:35456
	s_waitcnt lgkmcnt(3)
	v_mfma_f32_16x16x32_bf16 v[206:209], v[154:157], v[24:27], v[100:103]
	v_mfma_f32_16x16x32_bf16 v[212:215], v[154:157], v[36:39], v[84:87]
	s_waitcnt lgkmcnt(2)
	v_mfma_f32_16x16x32_bf16 v[154:157], v[158:161], v[24:27], v[104:107]
	v_mfma_f32_16x16x32_bf16 v[216:219], v[158:161], v[36:39], v[88:91]
	s_waitcnt lgkmcnt(1)
	v_mfma_f32_16x16x32_bf16 v[220:223], v[162:165], v[24:27], v[108:111]
	v_mfma_f32_16x16x32_bf16 v[224:227], v[162:165], v[36:39], v[92:95]
	s_waitcnt lgkmcnt(0)
	v_mfma_f32_16x16x32_bf16 v[228:231], v[166:169], v[24:27], v[112:115]
	v_mfma_f32_16x16x32_bf16 v[232:235], v[166:169], v[36:39], v[96:99]
	s_nop 1
	ds_read_b64_tr_b16 v[114:115], v176 offset:41472
	ds_read_b64_tr_b16 v[112:113], v176 offset:38912
	ds_read_b64_tr_b16 v[108:109], v176 offset:38944
	ds_read_b64_tr_b16 v[110:111], v176 offset:41504
	ds_read_b64_tr_b16 v[104:105], v176 offset:38976
	ds_read_b64_tr_b16 v[106:107], v176 offset:41536
	ds_read_b64_tr_b16 v[96:97], v176 offset:39008
	ds_read_b64_tr_b16 v[98:99], v176 offset:41568
	ds_read_b64_tr_b16 v[84:85], v176 offset:44032
	ds_read_b64_tr_b16 v[86:87], v176 offset:46592
	ds_read_b64_tr_b16 v[88:89], v176 offset:44064
	ds_read_b64_tr_b16 v[90:91], v176 offset:46624
	ds_read_b64_tr_b16 v[92:93], v176 offset:44096
	ds_read_b64_tr_b16 v[94:95], v176 offset:46656
	ds_read_b64_tr_b16 v[100:101], v176 offset:44128
	ds_read_b64_tr_b16 v[102:103], v176 offset:46688
	v_exp_f32_e32 v205, v206
	v_exp_f32_e32 v206, v207
	v_exp_f32_e32 v207, v208
	v_exp_f32_e32 v208, v209
	v_exp_f32_e32 v209, v154
	v_exp_f32_e32 v210, v155
	v_exp_f32_e32 v147, v156
	v_exp_f32_e32 v155, v157
	v_exp_f32_e32 v157, v220
	v_exp_f32_e32 v159, v221
	v_exp_f32_e32 v161, v222
	v_exp_f32_e32 v163, v223
	v_exp_f32_e32 v165, v228
	v_exp_f32_e32 v167, v229
	v_exp_f32_e32 v169, v230
	v_exp_f32_e32 v171, v231
	v_exp_f32_e32 v211, v212
	v_exp_f32_e32 v212, v213
	v_exp_f32_e32 v213, v214
	v_exp_f32_e32 v214, v215
	v_exp_f32_e32 v215, v216
	v_exp_f32_e32 v216, v217
	v_exp_f32_e32 v146, v218
	v_exp_f32_e32 v154, v219
	v_exp_f32_e32 v156, v224
	v_exp_f32_e32 v158, v225
	v_exp_f32_e32 v160, v226
	v_exp_f32_e32 v162, v227
	v_exp_f32_e32 v164, v232
	v_exp_f32_e32 v166, v233
	v_exp_f32_e32 v168, v234
	v_exp_f32_e32 v170, v235
	v_cvt_pk_bf16_f32 v218, v205, v206
	v_cvt_pk_bf16_f32 v219, v207, v208
	v_cvt_pk_bf16_f32 v220, v209, v210
	v_cvt_pk_bf16_f32 v221, v147, v155
	v_cvt_pk_bf16_f32 v222, v211, v212
	v_cvt_pk_bf16_f32 v223, v213, v214
	v_cvt_pk_bf16_f32 v224, v215, v216
	v_cvt_pk_bf16_f32 v225, v146, v154
	s_waitcnt lgkmcnt(14)
	v_mfma_f32_16x16x32_bf16 v[76:79], v[112:115], v[218:221], v[76:79]
	s_andn2_b64 vcc, exec, s[26:27]
	v_mfma_f32_16x16x32_bf16 v[112:115], v[112:115], v[222:225], v[80:83]
	s_waitcnt lgkmcnt(12)
	v_mfma_f32_16x16x32_bf16 v[226:229], v[108:111], v[218:221], v[72:75]
	v_mfma_f32_16x16x32_bf16 v[68:71], v[108:111], v[222:225], v[68:71]
	s_waitcnt lgkmcnt(10)
	v_mfma_f32_16x16x32_bf16 v[64:67], v[104:107], v[218:221], v[64:67]
	v_mfma_f32_16x16x32_bf16 v[104:107], v[104:107], v[222:225], v[10:13]
	s_waitcnt lgkmcnt(8)
	v_mfma_f32_16x16x32_bf16 v[108:111], v[96:99], v[218:221], v[6:9]
	v_cvt_pk_bf16_f32 v218, v156, v158
	v_cvt_pk_bf16_f32 v219, v160, v162
	v_cvt_pk_bf16_f32 v220, v164, v166
	v_mfma_f32_16x16x32_bf16 v[2:5], v[96:99], v[222:225], v[2:5]
	v_cvt_pk_bf16_f32 v96, v157, v159
	v_cvt_pk_bf16_f32 v97, v161, v163
	v_cvt_pk_bf16_f32 v98, v165, v167
	v_cvt_pk_bf16_f32 v99, v169, v171
	v_cvt_pk_bf16_f32 v221, v168, v170
	s_waitcnt lgkmcnt(6)
	v_mfma_f32_16x16x32_bf16 v[80:83], v[84:87], v[96:99], v[76:79]
	v_mfma_f32_16x16x32_bf16 v[72:75], v[84:87], v[218:221], v[112:115]
	s_waitcnt lgkmcnt(4)
	v_mfma_f32_16x16x32_bf16 v[76:79], v[88:91], v[96:99], v[226:229]
	v_mfma_f32_16x16x32_bf16 v[12:15], v[88:91], v[218:221], v[68:71]
	s_waitcnt lgkmcnt(2)
	v_mfma_f32_16x16x32_bf16 v[68:71], v[92:95], v[96:99], v[64:67]
	v_mfma_f32_16x16x32_bf16 v[8:11], v[92:95], v[218:221], v[104:107]
	s_waitcnt lgkmcnt(0)
	v_mfma_f32_16x16x32_bf16 v[64:67], v[100:103], v[96:99], v[108:111]
	v_mfma_f32_16x16x32_bf16 v[4:7], v[100:103], v[218:221], v[2:5]
	s_cbranch_vccnz .LBB0_1135
	s_and_saveexec_b64 s[26:27], s[40:41]
	s_nop 0
	v_add_u32_e32 v2, v174, v150
	ds_write_b128 v2, v[40:43]
	s_or_b64 exec, exec, s[26:27]
	s_and_saveexec_b64 s[26:27], s[48:49]
	s_cbranch_execz .LBB0_1134
	v_add_u32_e32 v2, v175, v152
	ds_write_b128 v2, v[44:47]
	s_branch .LBB0_1134
; template <int DQK, bool NA, bool SMAX, int LDV> ...
;     ...
;     if (it + 2 < nkt) {
;       const int kb = (it + 2) * 64 + ((it + 2) >= 4 ? koff : 0);
; #pragma unroll
;       for (int i = 0; i < NKC; ++i) rk_ld[i] = *(const u32x4*)(Kp + (size_t)(kb + kkey[i]) * ldk + kcc[i] * 8);
;       rv_ld = *(const u32x4*)(Vp + (size_t)(kb + vdv) * LDV + vcc * 8);
;     }
;     __builtin_amdgcn_sched_barrier(0);
;     const char* ks = smem + cur * STG;
;     const char* vs = ks + KBYTES;
;     f32x4 s[4][2];
; #pragma unroll
;     for (int kt = 0; kt < 4; ++kt) { s[kt][0] = (f32x4){0.f, 0.f, 0.f, 0.f}; s[kt][1] = (f32x4){0.f, 0.f, 0.f, 0.f}; }
; #pragma unroll
;     for (int ds = 0; ds < NDS; ++ds) {
;       bf16x8 kf[4];
; #pragma unroll
;       for (int kt = 0; kt < 4; ++kt) kf[kt] = *(const bf16x8*)(ks + (kt * 16 + fr) * KSTR + ds * 64 + fq * 16);
; #pragma unroll
;       for (int kt = 0; kt < 4; ++kt) {
;         s[kt][0] = __builtin_amdgcn_mfma_f32_16x16x32_bf16(kf[kt], qf[0][ds], s[kt][0], 0, 0, 0);
;         s[kt][1] = __builtin_amdgcn_mfma_f32_16x16x32_bf16(kf[kt], qf[1][ds], s[kt][1], 0, 0, 0);
;       }
;     }
;     bf16x8 vfr[2][4];
; #pragma unroll
;     for (int k2 = 0; k2 < 2; ++k2)
; #pragma unroll
;       for (int d = 0; d < 4; ++d) {
;         const char* vp = vs + (k2 * 32 + fq * 4 + (fr >> 2)) * VSTR + d * 32 + (fr & 3) * 8;
;         typedef short s16x4_t __attribute__((ext_vector_type(4)));
;         const s16x4_t lo = __builtin_amdgcn_ds_read_tr16_b64_v4i16((__attribute__((address_space(3))) s16x4_t*)(vp));
;         const s16x4_t hi = __builtin_amdgcn_ds_read_tr16_b64_v4i16((__attribute__((address_space(3))) s16x4_t*)(vp + 16 * VSTR));
;         vfr[k2][d] = __builtin_shufflevector(lo, hi, 0, 1, 2, 3, 4, 5, 6, 7);
;       }
.Lmla_y_1136:
	s_cmp_lt_u32 s19, 34
	s_cselect_b64 s[26:27], -1, 0
	s_cmp_gt_u32 s19, 33
	s_cselect_b64 s[4:5], -1, 0
	s_and_b64 vcc, exec, s[4:5]
	v_lshl_add_u64 v[156:157], s[20:21], 0, v[126:127]
	v_lshl_add_u64 v[154:155], s[20:21], 0, v[124:125]
	v_lshl_add_u64 v[146:147], s[20:21], 0, v[120:121]
	s_cbranch_vccnz .Lmla_y_1138
	v_add_co_u32_e32 v2, vcc, 0x1094d000, v156
	s_nop 1
	v_addc_co_u32_e32 v3, vcc, 0, v157, vcc
	v_add_co_u32_e32 v44, vcc, 0x1094d000, v154
	s_nop 1
	v_addc_co_u32_e32 v45, vcc, 0, v155, vcc
	global_load_dwordx4 v[40:43], v[2:3], off
	s_nop 0
	global_load_dwordx4 v[44:47], v[44:45], off
	v_add_co_u32_e32 v2, vcc, 0x1243d000, v146
	s_nop 1
	v_addc_co_u32_e32 v3, vcc, 0, v147, vcc
	global_load_dwordx4 v[52:55], v[2:3], off
.Lmla_y_1138:
	ds_read_b128 v[84:87], v0
	ds_read_b128 v[88:91], v0 offset:3584
	ds_read_b128 v[92:95], v0 offset:7168
	ds_read_b128 v[96:99], v0 offset:10752
	ds_read_b128 v[128:131], v0 offset:64
	ds_read_b128 v[132:135], v0 offset:3648
	ds_read_b128 v[136:139], v0 offset:7232
	ds_read_b128 v[140:143], v0 offset:10816
	s_waitcnt lgkmcnt(7)
	v_mfma_f32_16x16x32_bf16 v[100:103], v[84:87], v[16:19], v[244:247]
	v_mfma_f32_16x16x32_bf16 v[84:87], v[84:87], v[28:31], v[244:247]
	s_waitcnt lgkmcnt(6)
	v_mfma_f32_16x16x32_bf16 v[104:107], v[88:91], v[16:19], v[244:247]
	v_mfma_f32_16x16x32_bf16 v[88:91], v[88:91], v[28:31], v[244:247]
	s_waitcnt lgkmcnt(5)
	v_mfma_f32_16x16x32_bf16 v[108:111], v[92:95], v[16:19], v[244:247]
	v_mfma_f32_16x16x32_bf16 v[92:95], v[92:95], v[28:31], v[244:247]
	s_waitcnt lgkmcnt(4)
	v_mfma_f32_16x16x32_bf16 v[112:115], v[96:99], v[16:19], v[244:247]
	v_mfma_f32_16x16x32_bf16 v[96:99], v[96:99], v[28:31], v[244:247]
	s_waitcnt lgkmcnt(3)
	v_mfma_f32_16x16x32_bf16 v[100:103], v[128:131], v[20:23], v[100:103]
	v_mfma_f32_16x16x32_bf16 v[84:87], v[128:131], v[32:35], v[84:87]
	s_waitcnt lgkmcnt(2)
	v_mfma_f32_16x16x32_bf16 v[104:107], v[132:135], v[20:23], v[104:107]
	v_mfma_f32_16x16x32_bf16 v[88:91], v[132:135], v[32:35], v[88:91]
	s_waitcnt lgkmcnt(1)
	v_mfma_f32_16x16x32_bf16 v[108:111], v[136:139], v[20:23], v[108:111]
	v_mfma_f32_16x16x32_bf16 v[92:95], v[136:139], v[32:35], v[92:95]
	s_waitcnt lgkmcnt(0)
	v_mfma_f32_16x16x32_bf16 v[112:115], v[140:143], v[20:23], v[112:115]
	v_mfma_f32_16x16x32_bf16 v[96:99], v[140:143], v[32:35], v[96:99]
	ds_read_b128 v[128:131], v0 offset:128
	ds_read_b128 v[132:135], v0 offset:3712
	ds_read_b128 v[136:139], v0 offset:7296
	ds_read_b128 v[140:143], v0 offset:10880
	s_waitcnt lgkmcnt(3)
	v_mfma_f32_16x16x32_bf16 v[158:161], v[128:131], v[24:27], v[100:103]
	v_mfma_f32_16x16x32_bf16 v[162:165], v[128:131], v[36:39], v[84:87]
	s_waitcnt lgkmcnt(2)
	v_mfma_f32_16x16x32_bf16 v[128:131], v[132:135], v[24:27], v[104:107]
	v_mfma_f32_16x16x32_bf16 v[166:169], v[132:135], v[36:39], v[88:91]
	s_waitcnt lgkmcnt(1)
	v_mfma_f32_16x16x32_bf16 v[184:187], v[136:139], v[24:27], v[108:111]
	v_mfma_f32_16x16x32_bf16 v[206:209], v[136:139], v[36:39], v[92:95]
	s_waitcnt lgkmcnt(0)
	v_mfma_f32_16x16x32_bf16 v[210:213], v[140:143], v[24:27], v[112:115]
	v_mfma_f32_16x16x32_bf16 v[214:217], v[140:143], v[36:39], v[96:99]
	s_nop 1
	ds_read_b64_tr_b16 v[114:115], v176 offset:16896
	ds_read_b64_tr_b16 v[112:113], v176 offset:14336
	ds_read_b64_tr_b16 v[108:109], v176 offset:14368
	ds_read_b64_tr_b16 v[110:111], v176 offset:16928
	ds_read_b64_tr_b16 v[104:105], v176 offset:14400
	ds_read_b64_tr_b16 v[106:107], v176 offset:16960
	ds_read_b64_tr_b16 v[96:97], v176 offset:14432
	ds_read_b64_tr_b16 v[98:99], v176 offset:16992
	ds_read_b64_tr_b16 v[84:85], v176 offset:19456
	ds_read_b64_tr_b16 v[86:87], v176 offset:22016
	ds_read_b64_tr_b16 v[88:89], v176 offset:19488
	ds_read_b64_tr_b16 v[90:91], v176 offset:22048
	ds_read_b64_tr_b16 v[92:93], v176 offset:19520
	ds_read_b64_tr_b16 v[94:95], v176 offset:22080
	ds_read_b64_tr_b16 v[100:101], v176 offset:19552
	ds_read_b64_tr_b16 v[102:103], v176 offset:22112
	s_and_saveexec_b64 s[42:43], s[40:41]
	s_cbranch_execz .Lmla_y_1140
	v_add_u32_e32 v132, v174, v150
	s_waitcnt vmcnt(2)
	ds_write_b128 v132, v[48:51] offset:24576
.Lmla_y_1140:
	s_or_b64 exec, exec, s[42:43]
	s_and_saveexec_b64 s[42:43], s[48:49]
	s_cbranch_execz .Lmla_y_1142
	v_add_u32_e32 v132, v175, v152
	s_waitcnt vmcnt(1)
	ds_write_b128 v132, v[56:59] offset:24576

; template <int DQK, bool NA, bool SMAX, int LDV> ...
;     ...
;     f32x4 s[4][2];
; #pragma unroll
;     for (int kt = 0; kt < 4; ++kt) { s[kt][0] = (f32x4){0.f, 0.f, 0.f, 0.f}; s[kt][1] = (f32x4){0.f, 0.f, 0.f, 0.f}; }
; #pragma unroll
;     for (int ds = 0; ds < NDS; ++ds) {
;       bf16x8 kf[4];
; #pragma unroll
;       for (int kt = 0; kt < 4; ++kt) kf[kt] = *(const bf16x8*)(ks + (kt * 16 + fr) * KSTR + ds * 64 + fq * 16);
; #pragma unroll
;       for (int kt = 0; kt < 4; ++kt) {
;         s[kt][0] = __builtin_amdgcn_mfma_f32_16x16x32_bf16(kf[kt], qf[0][ds], s[kt][0], 0, 0, 0);
;         s[kt][1] = __builtin_amdgcn_mfma_f32_16x16x32_bf16(kf[kt], qf[1][ds], s[kt][1], 0, 0, 0);
;       }
;     }
;     bf16x8 vfr[2][4];
; #pragma unroll
;     for (int k2 = 0; k2 < 2; ++k2)
; #pragma unroll
;       for (int d = 0; d < 4; ++d) {
;         const char* vp = vs + (k2 * 32 + fq * 4 + (fr >> 2)) * VSTR + d * 32 + (fr & 3) * 8;
;         typedef short s16x4_t __attribute__((ext_vector_type(4)));
;         const s16x4_t lo = __builtin_amdgcn_ds_read_tr16_b64_v4i16((__attribute__((address_space(3))) s16x4_t*)(vp));
;         const s16x4_t hi = __builtin_amdgcn_ds_read_tr16_b64_v4i16((__attribute__((address_space(3))) s16x4_t*)(vp + 16 * VSTR));
;         vfr[k2][d] = __builtin_shufflevector(lo, hi, 0, 1, 2, 3, 4, 5, 6, 7);
;       }
;     ...
; #pragma unroll
;     for (int k2 = 0; k2 < 2; ++k2) {
;       bf16x8 pf[2];
; #pragma unroll
;       for (int qt = 0; qt < 2; ++qt) {
;         u32x4 u;
;         u[0] = cvt_pk_bf16(s[2 * k2][qt][0], s[2 * k2][qt][1]); u[1] = cvt_pk_bf16(s[2 * k2][qt][2], s[2 * k2][qt][3]);
;         u[2] = cvt_pk_bf16(s[2 * k2 + 1][qt][0], s[2 * k2 + 1][qt][1]); u[3] = cvt_pk_bf16(s[2 * k2 + 1][qt][2], s[2 * k2 + 1][qt][3]);
;         pf[qt] = __builtin_bit_cast(bf16x8, u);
;       }
; #pragma unroll
;       for (int d = 0; d < 4; ++d) {
;         o[d][0] = __builtin_amdgcn_mfma_f32_16x16x32_bf16(vfr[k2][d], pf[0], o[d][0], 0, 0, 0);
;         o[d][1] = __builtin_amdgcn_mfma_f32_16x16x32_bf16(vfr[k2][d], pf[1], o[d][1], 0, 0, 0);
;       }
;     }
;     if (more) {
;       char* nx = smem + (cur ^ 1) * STG;
; #pragma unroll
;       for (int i = 0; i < NKC; ++i) if (kval[i]) *(u32x4*)(nx + kkey[i] * KSTR + kcc[i] * 16) = rk_wr[i];
;       *(u32x4*)(nx + KBYTES + vdv * VSTR + vcc * 16) = rv_wr;
.Lmla_y_1144:
	v_exp_f32_e32 v177, v158
	v_exp_f32_e32 v178, v159
	v_exp_f32_e32 v179, v160
	v_exp_f32_e32 v180, v161
	v_exp_f32_e32 v181, v128
	v_exp_f32_e32 v182, v129
	v_exp_f32_e32 v183, v130
	v_exp_f32_e32 v129, v131
	v_exp_f32_e32 v131, v184
	v_exp_f32_e32 v133, v185
	v_exp_f32_e32 v135, v186
	v_exp_f32_e32 v137, v187
	v_exp_f32_e32 v139, v210
	v_exp_f32_e32 v141, v211
	v_exp_f32_e32 v143, v212
	v_exp_f32_e32 v145, v213
	v_exp_f32_e32 v184, v162
	v_exp_f32_e32 v185, v163
	v_exp_f32_e32 v186, v164
	v_exp_f32_e32 v187, v165
	v_exp_f32_e32 v189, v166
	v_exp_f32_e32 v203, v167
	v_exp_f32_e32 v204, v168
	v_exp_f32_e32 v128, v169
	v_exp_f32_e32 v130, v206
	v_exp_f32_e32 v132, v207
	v_exp_f32_e32 v134, v208
	v_exp_f32_e32 v136, v209
	v_exp_f32_e32 v138, v214
	v_exp_f32_e32 v140, v215
	v_exp_f32_e32 v142, v216
	v_exp_f32_e32 v144, v217
	v_cvt_pk_bf16_f32 v158, v177, v178
	v_cvt_pk_bf16_f32 v159, v179, v180
	v_cvt_pk_bf16_f32 v160, v181, v182
	v_cvt_pk_bf16_f32 v161, v183, v129
	v_cvt_pk_bf16_f32 v162, v184, v185
	v_cvt_pk_bf16_f32 v163, v186, v187
	v_cvt_pk_bf16_f32 v164, v189, v203
	v_cvt_pk_bf16_f32 v165, v204, v128
	s_waitcnt lgkmcnt(14)
	v_mfma_f32_16x16x32_bf16 v[80:83], v[112:115], v[158:161], v[80:83]
	v_mfma_f32_16x16x32_bf16 v[72:75], v[112:115], v[162:165], v[72:75]
	s_waitcnt lgkmcnt(12)
	v_mfma_f32_16x16x32_bf16 v[112:115], v[108:111], v[158:161], v[76:79]
	v_mfma_f32_16x16x32_bf16 v[12:15], v[108:111], v[162:165], v[12:15]
	s_waitcnt lgkmcnt(10)
	v_mfma_f32_16x16x32_bf16 v[108:111], v[104:107], v[158:161], v[68:71]
	v_mfma_f32_16x16x32_bf16 v[8:11], v[104:107], v[162:165], v[8:11]
	s_waitcnt lgkmcnt(8)
	v_mfma_f32_16x16x32_bf16 v[104:107], v[96:99], v[158:161], v[64:67]
	v_cvt_pk_bf16_f32 v158, v130, v132
	v_cvt_pk_bf16_f32 v159, v134, v136
	v_cvt_pk_bf16_f32 v160, v138, v140
	v_mfma_f32_16x16x32_bf16 v[2:5], v[96:99], v[162:165], v[4:7]
	v_cvt_pk_bf16_f32 v96, v131, v133
	v_cvt_pk_bf16_f32 v97, v135, v137
	v_cvt_pk_bf16_f32 v98, v139, v141
	v_cvt_pk_bf16_f32 v99, v143, v145
	v_cvt_pk_bf16_f32 v161, v142, v144
	s_waitcnt lgkmcnt(6)
	v_mfma_f32_16x16x32_bf16 v[76:79], v[84:87], v[96:99], v[80:83]
	v_mfma_f32_16x16x32_bf16 v[80:83], v[84:87], v[158:161], v[72:75]
	s_waitcnt lgkmcnt(4)
	v_mfma_f32_16x16x32_bf16 v[72:75], v[88:91], v[96:99], v[112:115]
	v_mfma_f32_16x16x32_bf16 v[68:71], v[88:91], v[158:161], v[12:15]
	s_waitcnt lgkmcnt(2)
	v_mfma_f32_16x16x32_bf16 v[64:67], v[92:95], v[96:99], v[108:111]
	v_mfma_f32_16x16x32_bf16 v[10:13], v[92:95], v[158:161], v[8:11]
	s_waitcnt lgkmcnt(0)
	v_mfma_f32_16x16x32_bf16 v[6:9], v[100:103], v[96:99], v[104:107]
	v_mfma_f32_16x16x32_bf16 v[2:5], v[100:103], v[158:161], v[2:5]
	ds_read_b128 v[84:87], v0 offset:24576
	ds_read_b128 v[88:91], v0 offset:28160
	ds_read_b128 v[92:95], v0 offset:31744
	ds_read_b128 v[96:99], v0 offset:35328
	ds_read_b128 v[154:157], v0 offset:24640
	ds_read_b128 v[158:161], v0 offset:28224
	ds_read_b128 v[162:165], v0 offset:31808
	ds_read_b128 v[166:169], v0 offset:35392
	s_waitcnt lgkmcnt(7)
	v_mfma_f32_16x16x32_bf16 v[100:103], v[84:87], v[16:19], v[244:247]
	v_mfma_f32_16x16x32_bf16 v[84:87], v[84:87], v[28:31], v[244:247]
	s_waitcnt lgkmcnt(6)
	v_mfma_f32_16x16x32_bf16 v[104:107], v[88:91], v[16:19], v[244:247]
	v_mfma_f32_16x16x32_bf16 v[88:91], v[88:91], v[28:31], v[244:247]
	s_waitcnt lgkmcnt(5)
	v_mfma_f32_16x16x32_bf16 v[108:111], v[92:95], v[16:19], v[244:247]
	v_mfma_f32_16x16x32_bf16 v[92:95], v[92:95], v[28:31], v[244:247]
	s_waitcnt lgkmcnt(4)
	v_mfma_f32_16x16x32_bf16 v[112:115], v[96:99], v[16:19], v[244:247]
	v_mfma_f32_16x16x32_bf16 v[96:99], v[96:99], v[28:31], v[244:247]
	s_waitcnt lgkmcnt(3)
	v_mfma_f32_16x16x32_bf16 v[100:103], v[154:157], v[20:23], v[100:103]
	v_mfma_f32_16x16x32_bf16 v[84:87], v[154:157], v[32:35], v[84:87]
	s_waitcnt lgkmcnt(2)
	v_mfma_f32_16x16x32_bf16 v[104:107], v[158:161], v[20:23], v[104:107]
	v_mfma_f32_16x16x32_bf16 v[88:91], v[158:161], v[32:35], v[88:91]
	s_waitcnt lgkmcnt(1)
	v_mfma_f32_16x16x32_bf16 v[108:111], v[162:165], v[20:23], v[108:111]
	v_mfma_f32_16x16x32_bf16 v[92:95], v[162:165], v[32:35], v[92:95]
	s_waitcnt lgkmcnt(0)
	v_mfma_f32_16x16x32_bf16 v[112:115], v[166:169], v[20:23], v[112:115]
	v_mfma_f32_16x16x32_bf16 v[96:99], v[166:169], v[32:35], v[96:99]
	ds_read_b128 v[154:157], v0 offset:24704
	ds_read_b128 v[158:161], v0 offset:28288
	ds_read_b128 v[162:165], v0 offset:31872
	ds_read_b128 v[166:169], v0 offset:35456
	s_waitcnt lgkmcnt(3)
	v_mfma_f32_16x16x32_bf16 v[206:209], v[154:157], v[24:27], v[100:103]
	v_mfma_f32_16x16x32_bf16 v[212:215], v[154:157], v[36:39], v[84:87]
	s_waitcnt lgkmcnt(2)
	v_mfma_f32_16x16x32_bf16 v[154:157], v[158:161], v[24:27], v[104:107]
	v_mfma_f32_16x16x32_bf16 v[216:219], v[158:161], v[36:39], v[88:91]
	s_waitcnt lgkmcnt(1)
	v_mfma_f32_16x16x32_bf16 v[220:223], v[162:165], v[24:27], v[108:111]
	v_mfma_f32_16x16x32_bf16 v[224:227], v[162:165], v[36:39], v[92:95]
	s_waitcnt lgkmcnt(0)
	v_mfma_f32_16x16x32_bf16 v[228:231], v[166:169], v[24:27], v[112:115]
	v_mfma_f32_16x16x32_bf16 v[232:235], v[166:169], v[36:39], v[96:99]
	s_nop 1
	ds_read_b64_tr_b16 v[114:115], v176 offset:41472
	ds_read_b64_tr_b16 v[112:113], v176 offset:38912
	ds_read_b64_tr_b16 v[108:109], v176 offset:38944
	ds_read_b64_tr_b16 v[110:111], v176 offset:41504
	ds_read_b64_tr_b16 v[104:105], v176 offset:38976
	ds_read_b64_tr_b16 v[106:107], v176 offset:41536
	ds_read_b64_tr_b16 v[96:97], v176 offset:39008
	ds_read_b64_tr_b16 v[98:99], v176 offset:41568
	ds_read_b64_tr_b16 v[84:85], v176 offset:44032
	ds_read_b64_tr_b16 v[86:87], v176 offset:46592
	ds_read_b64_tr_b16 v[88:89], v176 offset:44064
	ds_read_b64_tr_b16 v[90:91], v176 offset:46624
	ds_read_b64_tr_b16 v[92:93], v176 offset:44096
	ds_read_b64_tr_b16 v[94:95], v176 offset:46656
	ds_read_b64_tr_b16 v[100:101], v176 offset:44128
	ds_read_b64_tr_b16 v[102:103], v176 offset:46688
	s_andn2_b64 vcc, exec, s[26:27]
	s_cbranch_vccnz .Lmla_y_noW2
	s_and_saveexec_b64 s[26:27], s[40:41]
	s_nop 0
	v_add_u32_e32 v160, v174, v150
	ds_write_b128 v160, v[40:43]
	s_or_b64 exec, exec, s[26:27]
	s_and_saveexec_b64 s[26:27], s[48:49]
	s_cbranch_execz .Lmla_y_1134
	v_add_u32_e32 v160, v175, v152
	ds_write_b128 v160, v[44:47]

; DI unsigned cvt_pk_bf16(float lo, float hi) { f32x2_t v = {lo, hi}; bf16x2_t b = __builtin_convertvector(v, bf16x2_t); return __builtin_bit_cast(unsigned, b); }
; template <int DQK, bool NA, bool SMAX, int LDV> ...
;     ...
; #pragma unroll
;           for (int kt = 0; kt < 4; ++kt)
; #pragma unroll
;             for (int j = 0; j < 4; ++j) { const float pv = __builtin_amdgcn_exp2f(__builtin_fmaf(s[kt][qt][j], c1, -m0)); s[kt][qt][j] = pv; sum += pv; }
;         }
;         lrun[qt] += sum;
;     ...
; #pragma unroll
;     for (int k2 = 0; k2 < 2; ++k2) {
;       bf16x8 pf[2];
; #pragma unroll
;       for (int qt = 0; qt < 2; ++qt) {
;         u32x4 u;
;         u[0] = cvt_pk_bf16(s[2 * k2][qt][0], s[2 * k2][qt][1]); u[1] = cvt_pk_bf16(s[2 * k2][qt][2], s[2 * k2][qt][3]);
;         u[2] = cvt_pk_bf16(s[2 * k2 + 1][qt][0], s[2 * k2 + 1][qt][1]); u[3] = cvt_pk_bf16(s[2 * k2 + 1][qt][2], s[2 * k2 + 1][qt][3]);
;         pf[qt] = __builtin_bit_cast(bf16x8, u);
;       }
; #pragma unroll
;       for (int d = 0; d < 4; ++d) {
;         o[d][0] = __builtin_amdgcn_mfma_f32_16x16x32_bf16(vfr[k2][d], pf[0], o[d][0], 0, 0, 0);
;         o[d][1] = __builtin_amdgcn_mfma_f32_16x16x32_bf16(vfr[k2][d], pf[1], o[d][1], 0, 0, 0);
;       }
;     }
;     if (more) {
;       char* nx = smem + (cur ^ 1) * STG;
; #pragma unroll
;       for (int i = 0; i < NKC; ++i) if (kval[i]) *(u32x4*)(nx + kkey[i] * KSTR + kcc[i] * 16) = rk_wr[i];
;       *(u32x4*)(nx + KBYTES + vdv * VSTR + vcc * 16) = rv_wr;
;     }
;     __syncthreads();
;   };
;   for (int it = 0; it < nkt; it += 2) {
;     step(it, rkA, rvA, rkB, rvB);
;     if (it + 1 < nkt) step(it + 1, rkB, rvB, rkA, rvA);
;   }
.Lmla_y_noW2:
	s_waitcnt lgkmcnt(0)
	s_barrier
	v_exp_f32_e32 v205, v206
	v_exp_f32_e32 v206, v207
	v_exp_f32_e32 v207, v208
	v_exp_f32_e32 v208, v209
	v_exp_f32_e32 v209, v154
	v_exp_f32_e32 v210, v155
	v_exp_f32_e32 v147, v156
	v_exp_f32_e32 v155, v157
	v_exp_f32_e32 v157, v220
	v_exp_f32_e32 v159, v221
	v_exp_f32_e32 v161, v222
	v_exp_f32_e32 v163, v223
	v_exp_f32_e32 v165, v228
	v_exp_f32_e32 v167, v229
	v_exp_f32_e32 v169, v230
	v_exp_f32_e32 v171, v231
	v_exp_f32_e32 v211, v212
	v_exp_f32_e32 v212, v213
	v_exp_f32_e32 v213, v214
	v_exp_f32_e32 v214, v215
	v_exp_f32_e32 v215, v216
	v_exp_f32_e32 v216, v217
	v_exp_f32_e32 v146, v218
	v_exp_f32_e32 v154, v219
	v_exp_f32_e32 v156, v224
	v_exp_f32_e32 v158, v225
	v_exp_f32_e32 v160, v226
	v_exp_f32_e32 v162, v227
	v_exp_f32_e32 v164, v232
	v_exp_f32_e32 v166, v233
	v_exp_f32_e32 v168, v234
	v_exp_f32_e32 v170, v235
	v_cvt_pk_bf16_f32 v218, v205, v206
	v_cvt_pk_bf16_f32 v219, v207, v208
	v_cvt_pk_bf16_f32 v220, v209, v210
	v_cvt_pk_bf16_f32 v221, v147, v155
	v_cvt_pk_bf16_f32 v222, v211, v212
	v_cvt_pk_bf16_f32 v223, v213, v214
	v_cvt_pk_bf16_f32 v224, v215, v216
	v_cvt_pk_bf16_f32 v225, v146, v154
	s_waitcnt lgkmcnt(14)
	v_mfma_f32_16x16x32_bf16 v[76:79], v[112:115], v[218:221], v[76:79]
	v_mfma_f32_16x16x32_bf16 v[112:115], v[112:115], v[222:225], v[80:83]
	s_waitcnt lgkmcnt(12)
	v_mfma_f32_16x16x32_bf16 v[226:229], v[108:111], v[218:221], v[72:75]
	v_mfma_f32_16x16x32_bf16 v[68:71], v[108:111], v[222:225], v[68:71]
	s_waitcnt lgkmcnt(10)
	v_mfma_f32_16x16x32_bf16 v[64:67], v[104:107], v[218:221], v[64:67]
	v_mfma_f32_16x16x32_bf16 v[104:107], v[104:107], v[222:225], v[10:13]
	s_waitcnt lgkmcnt(8)
	v_mfma_f32_16x16x32_bf16 v[108:111], v[96:99], v[218:221], v[6:9]
	v_cvt_pk_bf16_f32 v218, v156, v158
	v_cvt_pk_bf16_f32 v219, v160, v162
	v_cvt_pk_bf16_f32 v220, v164, v166
	v_mfma_f32_16x16x32_bf16 v[2:5], v[96:99], v[222:225], v[2:5]
	v_cvt_pk_bf16_f32 v96, v157, v159
	v_cvt_pk_bf16_f32 v97, v161, v163
	v_cvt_pk_bf16_f32 v98, v165, v167
	v_cvt_pk_bf16_f32 v99, v169, v171
	v_cvt_pk_bf16_f32 v221, v168, v170
	s_waitcnt lgkmcnt(6)
	v_mfma_f32_16x16x32_bf16 v[80:83], v[84:87], v[96:99], v[76:79]
	v_mfma_f32_16x16x32_bf16 v[72:75], v[84:87], v[218:221], v[112:115]
	s_waitcnt lgkmcnt(4)
	v_mfma_f32_16x16x32_bf16 v[76:79], v[88:91], v[96:99], v[226:229]
	v_mfma_f32_16x16x32_bf16 v[12:15], v[88:91], v[218:221], v[68:71]
	s_waitcnt lgkmcnt(2)
	v_mfma_f32_16x16x32_bf16 v[68:71], v[92:95], v[96:99], v[64:67]
	v_mfma_f32_16x16x32_bf16 v[8:11], v[92:95], v[218:221], v[104:107]
	s_waitcnt lgkmcnt(0)
	v_mfma_f32_16x16x32_bf16 v[64:67], v[100:103], v[96:99], v[108:111]
	v_mfma_f32_16x16x32_bf16 v[4:7], v[100:103], v[218:221], v[2:5]
	s_nop 3
	s_nop 1
	v_add_f32_e32 v2, 0, v177
	v_add_f32_e32 v2, v178, v2
	v_add_f32_e32 v2, v179, v2
	v_add_f32_e32 v84, 0, v205
	v_add_f32_e32 v2, v180, v2
	v_add_f32_e32 v84, v206, v84
	v_add_f32_e32 v2, v181, v2
	v_add_f32_e32 v84, v207, v84
	v_add_f32_e32 v2, v182, v2
	v_add_f32_e32 v84, v208, v84
	v_add_f32_e32 v3, v183, v2
	v_add_f32_e32 v2, 0, v184
	v_add_f32_e32 v84, v209, v84
	v_add_f32_e32 v2, v185, v2
	v_add_f32_e32 v85, v210, v84
	v_add_f32_e32 v84, 0, v211
	v_add_f32_e32 v2, v186, v2
	v_add_f32_e32 v84, v212, v84
	v_add_f32_e32 v2, v187, v2
	v_add_f32_e32 v84, v213, v84
	v_add_f32_e32 v2, v189, v2
	v_add_f32_e32 v84, v214, v84
	v_add_f32_e32 v2, v203, v2
	v_add_f32_e32 v84, v215, v84
	v_add_f32_e32 v2, v204, v2
	v_add_f32_e32 v84, v216, v84
	v_pk_add_f32 v[2:3], v[128:129], v[2:3]
	v_pk_add_f32 v[84:85], v[146:147], v[84:85]
	v_pk_add_f32 v[2:3], v[130:131], v[2:3]
	v_pk_add_f32 v[84:85], v[154:155], v[84:85]
	v_pk_add_f32 v[2:3], v[132:133], v[2:3]
	v_pk_add_f32 v[84:85], v[156:157], v[84:85]
	v_pk_add_f32 v[2:3], v[134:135], v[2:3]
	v_pk_add_f32 v[84:85], v[158:159], v[84:85]
	v_pk_add_f32 v[2:3], v[136:137], v[2:3]
	v_pk_add_f32 v[84:85], v[160:161], v[84:85]
	v_pk_add_f32 v[2:3], v[138:139], v[2:3]
	v_pk_add_f32 v[84:85], v[162:163], v[84:85]
	v_pk_add_f32 v[2:3], v[140:141], v[2:3]
	v_pk_add_f32 v[84:85], v[164:165], v[84:85]
	v_pk_add_f32 v[2:3], v[142:143], v[2:3]
	v_pk_add_f32 v[84:85], v[166:167], v[84:85]
	v_pk_add_f32 v[2:3], v[144:145], v[2:3]
	v_pk_add_f32 v[84:85], v[168:169], v[84:85]
	v_pk_add_f32 v[2:3], v[122:123], v[2:3]
	v_pk_add_f32 v[84:85], v[170:171], v[84:85]
	s_add_i32 s19, s19, 2
	v_pk_add_f32 v[122:123], v[2:3], v[84:85]
	v_lshl_add_u64 v[120:121], v[120:121], 0, s[24:25]
	v_lshl_add_u64 v[124:125], v[124:125], 0, s[16:17]
	s_andn2_b64 vcc, exec, s[4:5]
	v_lshl_add_u64 v[126:127], v[126:127], 0, s[16:17]
	s_cbranch_vccz .LBB0_992
	s_branch .Lmla_y_1136
